# ADIFF fast loop: weighted spacing + only half of the S1 second-half softmax carried into the next S0 chain gaps (keeps those gaps within the 32-cycle MFMA budget)
# baseline (speedup 1.0000x reference)
; __device__ __forceinline__ void diff_attn_phase(const Params& p, LAS unsigned char* lds) {
;     ...
;         auto issue = [&](int ch, int stg) {
;             const char* kg = (const char*)(kp + (tokb + 64 * ch) * ld); const char* vg = (const char*)(vp + (tokb + 64 * ch) * ld);
;             LAS unsigned char* sb = lds + stg * STG;
; #pragma unroll
;             for (int i = 0; i < 2; ++i) { unsigned o = doff[i]; asm volatile("" : "+v"(o));
;                 __builtin_amdgcn_global_load_lds((const void*)(kg + o), (LAS void*)(sb + dlds[i]), 16, 0, 0);
;                 __builtin_amdgcn_global_load_lds((const void*)(vg + o), (LAS void*)(sb + 16384 + dlds[i]), 16, 0, 0); }
;         };
;         issue(0, 0); issue(1, 1);
;         int s_cur = 0, s_nn = 2;
;         for (int ch = 0; ch < NCH; ++ch) {
;             if (ch + 1 < NCH) asm volatile("s_waitcnt vmcnt(4)" ::: "memory"); else asm volatile("s_waitcnt vmcnt(0)" ::: "memory");
;             __builtin_amdgcn_s_barrier(); asm volatile("" ::: "memory");
;             if (ch + 2 < NCH) issue(ch + 2, s_nn);
;             const LAS unsigned char* Ksb = lds + s_cur * STG; const LAS unsigned char* Vsb = Ksb + 16384;
;             s_nn = s_cur; s_cur = (s_cur == 2) ? 0 : s_cur + 1;
; #pragma clang loop unroll(disable)
;             for (int u = 0; u < 2; ++u) {
;                 const LAS unsigned char* Ku = Ksb + u * 8192; const LAS unsigned char* Vu = Vsb + u * 8192;
;                 int kxl = kx, vb0l = vb0, vb1l = vb1; asm volatile("" : "+v"(kxl), "+v"(vb0l), "+v"(vb1l));
;                 bf16x8 kf[4];
; #pragma unroll
;                 for (int ks = 0; ks < 4; ++ks) kf[ks] = *(const LAS bf16x8*)(Ku + kbase + (kxl ^ (32 * ks)));
;                 bf16x8 P[2][2];
; #pragma unroll
;                 for (int r = 0; r < 2; ++r) {
;                     f32x16 S;
; #pragma unroll
;                     for (int i = 0; i < 16; ++i) S[i] = 0.f;
; #pragma unroll
;                     for (int ks = 0; ks < 4; ++ks) S = __builtin_amdgcn_mfma_f32_32x32x16_bf16(kf[ks], qf[r][ks], S, 0, 0, 0);
;                     S = __builtin_amdgcn_mfma_f32_32x32x16_bf16(kone, qm[r], S, 0, 0, 0);
; #pragma unroll
;                     for (int i = 0; i < 16; ++i) S[i] = __builtin_amdgcn_exp2f(S[i]);
;                     l[r] += sum16(S);
;                     P[r][0] = pack8(S, 0); P[r][1] = pack8(S, 8);
;                 }
; #pragma unroll
.Lfa_entry:
	s_waitcnt lgkmcnt(0)
	v_readfirstlane_b32 s34, v242
	s_movk_i32 s47, 0x60
	s_waitcnt vmcnt(4)
	s_barrier
	s_add_i32 s2, s29, 2
	s_lshl_b32 s10, s2, 6
	s_add_u32 s10, s26, s10
	s_addc_u32 s11, s27, 0
	s_lshl_b64 s[10:11], s[10:11], 13
	s_add_u32 s42, s25, s10
	s_addc_u32 s43, s28, s11
	s_add_u32 s10, s22, s10
	s_addc_u32 s11, s23, s11
	s_and_b32 s2, s2, 3
	s_lshl_b32 s2, s2, 15
	s_add_i32 s2, s2, s34
	s_mov_b32 m0, s2
	s_add_i32 s35, s2, 0x4000
	global_load_lds_dwordx4 v241, s[42:43]
	s_mov_b32 m0, s35
	s_add_i32 s35, s2, 0x2000
	global_load_lds_dwordx4 v241, s[10:11]
	s_mov_b32 m0, s35
	s_add_i32 s35, s2, 0x6000
	global_load_lds_dwordx4 v243, s[42:43]
	s_mov_b32 m0, s35
	s_nop 0
	global_load_lds_dwordx4 v243, s[10:11]
	v_mov_b32_e32 v1, v245
	v_mov_b32_e32 v234, v247
	v_mov_b32_e32 v235, v248
	v_xor_b32_e32 v237, 64, v247
	v_xor_b32_e32 v236, 64, v248
	v_xor_b32_e32 v238, 0x80, v247
	v_xor_b32_e32 v239, 0x80, v248
	v_xor_b32_e32 v250, 0xc0, v247
	v_xor_b32_e32 v251, 0xc0, v248
	v_add_u32_e32 v198, v246, v1
	ds_read_b128 v[198:201], v198
	v_xad_u32 v202, v246, 32, v1
	ds_read_b128 v[202:205], v202
	v_xad_u32 v208, v246, 64, v1
	ds_read_b128 v[208:211], v208
	v_xad_u32 v230, v246, s47, v1
	ds_read_b128 v[230:233], v230
	s_waitcnt lgkmcnt(3)
	v_mfma_f32_32x32x16_bf16 v[146:161], v[198:201], v[166:169], 0
	v_mfma_f32_32x32x16_bf16 v[130:145], v[198:201], v[182:185], 0
	v_add_u32_e32 v198, v246, v1
	ds_read_b128 v[198:201], v198 offset:8192
	s_waitcnt lgkmcnt(3)
	v_mfma_f32_32x32x16_bf16 v[146:161], v[202:205], v[170:173], v[146:161]
	v_mfma_f32_32x32x16_bf16 v[130:145], v[202:205], v[186:189], v[130:145]
	v_xad_u32 v202, v246, 32, v1
	ds_read_b128 v[202:205], v202 offset:8192
	s_waitcnt lgkmcnt(3)
	v_mfma_f32_32x32x16_bf16 v[146:161], v[208:211], v[174:177], v[146:161]
	v_mfma_f32_32x32x16_bf16 v[130:145], v[208:211], v[190:193], v[130:145]
	v_xad_u32 v208, v246, 64, v1
	ds_read_b128 v[208:211], v208 offset:8192
	s_waitcnt lgkmcnt(3)
	v_mfma_f32_32x32x16_bf16 v[146:161], v[230:233], v[178:181], v[146:161]
	v_mfma_f32_32x32x16_bf16 v[130:145], v[230:233], v[194:197], v[130:145]
	v_xad_u32 v230, v246, s47, v1
	ds_read_b128 v[230:233], v230 offset:8192
	s_nop 7
	s_nop 1
	v_exp_f32_e32 v146, v146
	v_exp_f32_e32 v147, v147
	v_exp_f32_e32 v148, v148
	v_exp_f32_e32 v149, v149
	v_add_f32_e32 v213, v213, v146
	v_add_f32_e32 v213, v213, v147
	v_add_f32_e32 v213, v213, v148
	v_add_f32_e32 v213, v213, v149
	v_exp_f32_e32 v150, v150
	v_exp_f32_e32 v151, v151
	v_exp_f32_e32 v152, v152
	v_exp_f32_e32 v153, v153
	v_add_f32_e32 v213, v213, v150
	v_add_f32_e32 v213, v213, v151
	v_add_f32_e32 v213, v213, v152
	v_add_f32_e32 v213, v213, v153
	v_exp_f32_e32 v154, v154
	v_exp_f32_e32 v155, v155
	v_exp_f32_e32 v156, v156
	v_exp_f32_e32 v157, v157
	v_add_f32_e32 v213, v213, v154
	v_add_f32_e32 v213, v213, v155
	v_add_f32_e32 v213, v213, v156
	v_add_f32_e32 v213, v213, v157
	v_exp_f32_e32 v158, v158
	v_exp_f32_e32 v159, v159
	v_exp_f32_e32 v160, v160
	v_exp_f32_e32 v161, v161
	v_add_f32_e32 v213, v213, v158
	v_add_f32_e32 v213, v213, v159
	v_add_f32_e32 v213, v213, v160
	v_add_f32_e32 v213, v213, v161
	v_exp_f32_e32 v130, v130
	v_exp_f32_e32 v131, v131
	v_exp_f32_e32 v132, v132
	v_exp_f32_e32 v133, v133
	v_add_f32_e32 v212, v212, v130
	v_add_f32_e32 v212, v212, v131
	v_add_f32_e32 v212, v212, v132
	v_add_f32_e32 v212, v212, v133
	v_exp_f32_e32 v134, v134
	v_exp_f32_e32 v135, v135
	v_exp_f32_e32 v136, v136
	v_exp_f32_e32 v137, v137
	v_add_f32_e32 v212, v212, v134
	v_add_f32_e32 v212, v212, v135
	v_add_f32_e32 v212, v212, v136
	v_add_f32_e32 v212, v212, v137
	v_cvt_pk_bf16_f32 v214, v146, v147
	v_cvt_pk_bf16_f32 v215, v148, v149
	v_cvt_pk_bf16_f32 v216, v150, v151
	v_cvt_pk_bf16_f32 v217, v152, v153
	v_cvt_pk_bf16_f32 v218, v130, v131
	v_cvt_pk_bf16_f32 v219, v132, v133
	v_cvt_pk_bf16_f32 v220, v134, v135
	v_cvt_pk_bf16_f32 v221, v136, v137
	v_cvt_pk_bf16_f32 v222, v154, v155
	v_cvt_pk_bf16_f32 v223, v156, v157
	v_cvt_pk_bf16_f32 v224, v158, v159
	v_cvt_pk_bf16_f32 v225, v160, v161
	v_exp_f32_e32 v138, v138
	v_exp_f32_e32 v139, v139
	v_exp_f32_e32 v140, v140
	v_exp_f32_e32 v141, v141
	v_add_f32_e32 v212, v212, v138
	v_add_f32_e32 v212, v212, v139
	v_add_f32_e32 v212, v212, v140
	v_add_f32_e32 v212, v212, v141
; #define LAS __attribute__((address_space(3)))
; __device__ __forceinline__ void diff_attn_phase(const Params& p, LAS unsigned char* lds) {
;     ...
;                 for (int ks = 0; ks < 4; ++ks) kf[ks] = *(const LAS bf16x8*)(Ku + kbase + (kxl ^ (32 * ks)));
;                 bf16x8 P[2][2];
; #pragma unroll
;                 for (int r = 0; r < 2; ++r) {
;                     f32x16 S;
; #pragma unroll
;                     for (int i = 0; i < 16; ++i) S[i] = 0.f;
; #pragma unroll
;                     for (int ks = 0; ks < 4; ++ks) S = __builtin_amdgcn_mfma_f32_32x32x16_bf16(kf[ks], qf[r][ks], S, 0, 0, 0);
;                     S = __builtin_amdgcn_mfma_f32_32x32x16_bf16(kone, qm[r], S, 0, 0, 0);
; #pragma unroll
;                     for (int i = 0; i < 16; ++i) S[i] = __builtin_amdgcn_exp2f(S[i]);
;                     l[r] += sum16(S);
;                     P[r][0] = pack8(S, 0); P[r][1] = pack8(S, 8);
;                 }
; #pragma unroll
;                 for (int t = 0; t < 4; ++t) {
;                     const LAS unsigned char* a0 = Vu + (vb0l ^ (64 * t)); const LAS unsigned char* a1 = Vu + (vb1l ^ (64 * t));
;                     const bf16x8 v0 = tr_pair(a0, a1), v1 = tr_pair(a0 + 4096, a1 + 4096);
;                     O[0][t] = __builtin_amdgcn_mfma_f32_32x32x16_bf16(v0, P[0][0], O[0][t], 0, 0, 0);
;                     O[1][t] = __builtin_amdgcn_mfma_f32_32x32x16_bf16(v0, P[1][0], O[1][t], 0, 0, 0);
;                     O[0][t] = __builtin_amdgcn_mfma_f32_32x32x16_bf16(v1, P[0][1], O[0][t], 0, 0, 0);
;                     O[1][t] = __builtin_amdgcn_mfma_f32_32x32x16_bf16(v1, P[1][1], O[1][t], 0, 0, 0);
.Lfb_loopF:
	s_waitcnt lgkmcnt(3)
	v_mfma_f32_32x32x16_bf16 v[146:161], v[198:201], v[166:169], 0
	v_exp_f32_e32 v142, v142
	v_exp_f32_e32 v143, v143
	s_waitcnt lgkmcnt(2)
	v_mfma_f32_32x32x16_bf16 v[146:161], v[202:205], v[170:173], v[146:161]
	v_exp_f32_e32 v144, v144
	v_exp_f32_e32 v145, v145
	s_waitcnt lgkmcnt(1)
	v_mfma_f32_32x32x16_bf16 v[146:161], v[208:211], v[174:177], v[146:161]
	v_add_f32_e32 v212, v212, v142
	v_add_f32_e32 v212, v212, v143
	v_add_f32_e32 v212, v212, v144
	v_add_f32_e32 v212, v212, v145
	s_waitcnt lgkmcnt(0)
	v_mfma_f32_32x32x16_bf16 v[146:161], v[230:233], v[178:181], v[146:161]
	v_cvt_pk_bf16_f32 v226, v138, v139
	v_cvt_pk_bf16_f32 v227, v140, v141
	v_cvt_pk_bf16_f32 v228, v142, v143
	v_cvt_pk_bf16_f32 v229, v144, v145
	v_mfma_f32_32x32x16_bf16 v[130:145], v[198:201], v[182:185], 0
	ds_read_b64_tr_b16 v[198:199], v234 offset:16384
	ds_read_b64_tr_b16 v[200:201], v235 offset:16384
	v_mfma_f32_32x32x16_bf16 v[130:145], v[202:205], v[186:189], v[130:145]
	ds_read_b64_tr_b16 v[202:203], v237 offset:16384
	ds_read_b64_tr_b16 v[204:205], v236 offset:16384
	v_mfma_f32_32x32x16_bf16 v[130:145], v[208:211], v[190:193], v[130:145]
	ds_read_b64_tr_b16 v[208:209], v238 offset:16384
	ds_read_b64_tr_b16 v[210:211], v239 offset:16384
	v_exp_f32_e32 v146, v146
	v_exp_f32_e32 v147, v147
	v_exp_f32_e32 v148, v148
	v_mfma_f32_32x32x16_bf16 v[130:145], v[230:233], v[194:197], v[130:145]
	ds_read_b64_tr_b16 v[230:231], v250 offset:16384
	ds_read_b64_tr_b16 v[232:233], v251 offset:16384
	v_exp_f32_e32 v149, v149
	v_add_f32_e32 v213, v213, v146
	v_add_f32_e32 v213, v213, v147
	v_add_f32_e32 v213, v213, v148
	v_add_f32_e32 v213, v213, v149
	s_waitcnt lgkmcnt(6)
	v_mfma_f32_32x32x16_bf16 v[114:129], v[198:201], v[214:217], v[114:129]
	v_exp_f32_e32 v150, v150
	v_exp_f32_e32 v151, v151
	v_exp_f32_e32 v152, v152
	v_mfma_f32_32x32x16_bf16 v[50:65], v[198:201], v[218:221], v[50:65]
	ds_read_b64_tr_b16 v[198:199], v234 offset:20480
	ds_read_b64_tr_b16 v[200:201], v235 offset:20480
	v_exp_f32_e32 v153, v153
	v_add_f32_e32 v213, v213, v150
	v_add_f32_e32 v213, v213, v151
	v_add_f32_e32 v213, v213, v152
	s_waitcnt lgkmcnt(6)
	v_mfma_f32_32x32x16_bf16 v[98:113], v[202:205], v[214:217], v[98:113]
	v_add_f32_e32 v213, v213, v153
	v_exp_f32_e32 v154, v154
	v_exp_f32_e32 v155, v155
	v_mfma_f32_32x32x16_bf16 v[34:49], v[202:205], v[218:221], v[34:49]
	ds_read_b64_tr_b16 v[202:203], v237 offset:20480
	ds_read_b64_tr_b16 v[204:205], v236 offset:20480
	v_exp_f32_e32 v156, v156
	v_exp_f32_e32 v157, v157
	v_add_f32_e32 v213, v213, v154
	s_waitcnt lgkmcnt(6)
	v_mfma_f32_32x32x16_bf16 v[82:97], v[208:211], v[214:217], v[82:97]
	v_add_f32_e32 v213, v213, v155
	v_add_f32_e32 v213, v213, v156
	v_add_f32_e32 v213, v213, v157
	v_exp_f32_e32 v158, v158
	v_mfma_f32_32x32x16_bf16 v[18:33], v[208:211], v[218:221], v[18:33]
	ds_read_b64_tr_b16 v[208:209], v238 offset:20480
	ds_read_b64_tr_b16 v[210:211], v239 offset:20480
	v_exp_f32_e32 v159, v159
	v_exp_f32_e32 v160, v160
	v_exp_f32_e32 v161, v161
	s_waitcnt lgkmcnt(6)
	v_mfma_f32_32x32x16_bf16 v[66:81], v[230:233], v[214:217], v[66:81]
	v_add_f32_e32 v213, v213, v158
	v_add_f32_e32 v213, v213, v159
	v_add_f32_e32 v213, v213, v160
	v_add_f32_e32 v213, v213, v161
	v_exp_f32_e32 v130, v130
	v_mfma_f32_32x32x16_bf16 v[2:17], v[230:233], v[218:221], v[2:17]
	ds_read_b64_tr_b16 v[230:231], v250 offset:20480
	ds_read_b64_tr_b16 v[232:233], v251 offset:20480
	v_exp_f32_e32 v131, v131
	v_exp_f32_e32 v132, v132
	v_exp_f32_e32 v133, v133
	s_cmpk_eq_u32 s29, 0x7f
	s_cbranch_scc1 .Lfb_last0F
	s_cmpk_eq_u32 s29, 0x7e
	s_cbranch_scc1 .Lfb_w0F
	s_waitcnt vmcnt(4)
	s_branch .Lfb_w1F

; __device__ __forceinline__ void diff_attn_phase(const Params& p, LAS unsigned char* lds) {
;     ...
;         auto issue = [&](int ch, int stg) {
;             const char* kg = (const char*)(kp + (tokb + 64 * ch) * ld); const char* vg = (const char*)(vp + (tokb + 64 * ch) * ld);
;             LAS unsigned char* sb = lds + stg * STG;
; #pragma unroll
;             for (int i = 0; i < 2; ++i) { unsigned o = doff[i]; asm volatile("" : "+v"(o));
;                 __builtin_amdgcn_global_load_lds((const void*)(kg + o), (LAS void*)(sb + dlds[i]), 16, 0, 0);
;                 __builtin_amdgcn_global_load_lds((const void*)(vg + o), (LAS void*)(sb + 16384 + dlds[i]), 16, 0, 0); }
;         };
;         issue(0, 0); issue(1, 1);
;         int s_cur = 0, s_nn = 2;
;         for (int ch = 0; ch < NCH; ++ch) {
;             if (ch + 1 < NCH) asm volatile("s_waitcnt vmcnt(4)" ::: "memory"); else asm volatile("s_waitcnt vmcnt(0)" ::: "memory");
;             __builtin_amdgcn_s_barrier(); asm volatile("" ::: "memory");
;             if (ch + 2 < NCH) issue(ch + 2, s_nn);
;             const LAS unsigned char* Ksb = lds + s_cur * STG; const LAS unsigned char* Vsb = Ksb + 16384;
;             s_nn = s_cur; s_cur = (s_cur == 2) ? 0 : s_cur + 1;
; #pragma clang loop unroll(disable)
;             for (int u = 0; u < 2; ++u) {
;                 const LAS unsigned char* Ku = Ksb + u * 8192; const LAS unsigned char* Vu = Vsb + u * 8192;
;                 int kxl = kx, vb0l = vb0, vb1l = vb1; asm volatile("" : "+v"(kxl), "+v"(vb0l), "+v"(vb1l));
;                 bf16x8 kf[4];
; #pragma unroll
;                 for (int ks = 0; ks < 4; ++ks) kf[ks] = *(const LAS bf16x8*)(Ku + kbase + (kxl ^ (32 * ks)));
;                 bf16x8 P[2][2];
; #pragma unroll
;                 for (int r = 0; r < 2; ++r) {
;                     f32x16 S;
; #pragma unroll
;                     for (int i = 0; i < 16; ++i) S[i] = 0.f;
; #pragma unroll
;                     for (int ks = 0; ks < 4; ++ks) S = __builtin_amdgcn_mfma_f32_32x32x16_bf16(kf[ks], qf[r][ks], S, 0, 0, 0);
;                     S = __builtin_amdgcn_mfma_f32_32x32x16_bf16(kone, qm[r], S, 0, 0, 0);
; #pragma unroll
;                     for (int i = 0; i < 16; ++i) S[i] = __builtin_amdgcn_exp2f(S[i]);
;                     l[r] += sum16(S);
;                     P[r][0] = pack8(S, 0); P[r][1] = pack8(S, 8);
;                 }
; #pragma unroll
.Lfb_w1F:
	s_barrier
	s_add_i32 s2, s29, 1
	s_and_b32 s2, s2, 3
	s_mov_b32 s37, 0x8000
	s_cmp_eq_u32 s2, 0
	s_cselect_b32 s37, 0xfffe8000, s37
	v_add_u32_e32 v1, s37, v1
	s_add_i32 s2, s29, 3
	s_lshl_b32 s10, s2, 6
	s_add_u32 s10, s26, s10
	s_addc_u32 s11, s27, 0
	s_lshl_b64 s[10:11], s[10:11], 13
	s_add_u32 s42, s25, s10
	s_addc_u32 s43, s28, s11
	s_add_u32 s10, s22, s10
	s_addc_u32 s11, s23, s11
	s_and_b32 s2, s2, 3
	s_lshl_b32 s2, s2, 15
	s_add_i32 s2, s2, s34
	s_waitcnt lgkmcnt(6)
	v_mfma_f32_32x32x16_bf16 v[114:129], v[198:201], v[222:225], v[114:129]
	v_add_f32_e32 v212, v212, v130
	v_add_f32_e32 v212, v212, v131
	v_add_f32_e32 v212, v212, v132
	v_add_f32_e32 v212, v212, v133
	v_exp_f32_e32 v134, v134
	v_mfma_f32_32x32x16_bf16 v[50:65], v[198:201], v[226:229], v[50:65]
	v_add_u32_e32 v198, v246, v1
	ds_read_b128 v[198:201], v198
	v_exp_f32_e32 v135, v135
	v_exp_f32_e32 v136, v136
	v_exp_f32_e32 v137, v137
	s_cmpk_gt_u32 s29, 0x7c
	s_cbranch_scc1 .Lfb_nd0F
	s_mov_b32 m0, s2
	s_nop 0
	global_load_lds_dwordx4 v241, s[42:43]
.Lfb_nd0F:
	s_waitcnt lgkmcnt(5)
	v_mfma_f32_32x32x16_bf16 v[98:113], v[202:205], v[222:225], v[98:113]
	v_add_f32_e32 v212, v212, v134
	v_add_f32_e32 v212, v212, v135
	v_add_f32_e32 v212, v212, v136
	v_add_f32_e32 v212, v212, v137
	v_mfma_f32_32x32x16_bf16 v[34:49], v[202:205], v[226:229], v[34:49]
	v_xad_u32 v202, v246, 32, v1
	ds_read_b128 v[202:205], v202
	v_cvt_pk_bf16_f32 v214, v146, v147
	v_cvt_pk_bf16_f32 v215, v148, v149
	v_cvt_pk_bf16_f32 v216, v150, v151
	v_cvt_pk_bf16_f32 v217, v152, v153
	s_cmpk_gt_u32 s29, 0x7c
	s_cbranch_scc1 .Lfb_nd1F
	s_add_i32 s35, s2, 0x4000
	s_mov_b32 m0, s35
	s_nop 0
	global_load_lds_dwordx4 v241, s[10:11]
.Lfb_nd1F:
	s_waitcnt lgkmcnt(4)
	v_mfma_f32_32x32x16_bf16 v[82:97], v[208:211], v[222:225], v[82:97]
	v_cvt_pk_bf16_f32 v218, v130, v131
	v_cvt_pk_bf16_f32 v219, v132, v133
	v_cvt_pk_bf16_f32 v220, v134, v135
	v_cvt_pk_bf16_f32 v221, v136, v137
	v_mfma_f32_32x32x16_bf16 v[18:33], v[208:211], v[226:229], v[18:33]
	v_xad_u32 v208, v246, 64, v1
	ds_read_b128 v[208:211], v208
	v_exp_f32_e32 v138, v138
	v_exp_f32_e32 v139, v139
	s_cmpk_gt_u32 s29, 0x7c
	s_cbranch_scc1 .Lfb_nd2F
	s_add_i32 s35, s2, 0x2000
	s_mov_b32 m0, s35
	s_nop 0
	global_load_lds_dwordx4 v243, s[42:43]
.Lfb_nd2F:
	s_waitcnt lgkmcnt(3)
	v_mfma_f32_32x32x16_bf16 v[66:81], v[230:233], v[222:225], v[66:81]
	v_exp_f32_e32 v140, v140
	v_exp_f32_e32 v141, v141
	v_add_f32_e32 v212, v212, v138
	v_add_f32_e32 v212, v212, v139
	v_add_f32_e32 v212, v212, v140
	v_add_f32_e32 v212, v212, v141
	v_cvt_pk_bf16_f32 v222, v154, v155
	v_cvt_pk_bf16_f32 v223, v156, v157
	v_cvt_pk_bf16_f32 v224, v158, v159
	v_cvt_pk_bf16_f32 v225, v160, v161
	v_mfma_f32_32x32x16_bf16 v[2:17], v[230:233], v[226:229], v[2:17]
	v_xad_u32 v230, v246, s47, v1
	ds_read_b128 v[230:233], v230
	s_cmpk_gt_u32 s29, 0x7c
	s_cbranch_scc1 .Lfb_nd3F
	s_add_i32 s35, s2, 0x6000
	s_mov_b32 m0, s35
	s_nop 0
	global_load_lds_dwordx4 v243, s[10:11]
.Lfb_nd3F:
	s_waitcnt lgkmcnt(3)
	v_mfma_f32_32x32x16_bf16 v[146:161], v[198:201], v[166:169], 0
	v_exp_f32_e32 v142, v142
	v_exp_f32_e32 v143, v143
	s_waitcnt lgkmcnt(2)
	v_mfma_f32_32x32x16_bf16 v[146:161], v[202:205], v[170:173], v[146:161]
	v_exp_f32_e32 v144, v144
	v_exp_f32_e32 v145, v145
	s_waitcnt lgkmcnt(1)
	v_mfma_f32_32x32x16_bf16 v[146:161], v[208:211], v[174:177], v[146:161]
	v_add_f32_e32 v212, v212, v142
	v_add_f32_e32 v212, v212, v143
	v_add_f32_e32 v212, v212, v144
	v_add_f32_e32 v212, v212, v145
	s_waitcnt lgkmcnt(0)
	v_mfma_f32_32x32x16_bf16 v[146:161], v[230:233], v[178:181], v[146:161]
	v_cvt_pk_bf16_f32 v226, v138, v139
	v_cvt_pk_bf16_f32 v227, v140, v141
	v_cvt_pk_bf16_f32 v228, v142, v143
	v_cvt_pk_bf16_f32 v229, v144, v145
	v_mfma_f32_32x32x16_bf16 v[130:145], v[198:201], v[182:185], 0
	ds_read_b64_tr_b16 v[198:199], v234 offset:24576
	ds_read_b64_tr_b16 v[200:201], v235 offset:24576
	v_mfma_f32_32x32x16_bf16 v[130:145], v[202:205], v[186:189], v[130:145]
	ds_read_b64_tr_b16 v[202:203], v237 offset:24576
	ds_read_b64_tr_b16 v[204:205], v236 offset:24576
	v_mfma_f32_32x32x16_bf16 v[130:145], v[208:211], v[190:193], v[130:145]
	ds_read_b64_tr_b16 v[208:209], v238 offset:24576
	ds_read_b64_tr_b16 v[210:211], v239 offset:24576
	v_exp_f32_e32 v146, v146
	v_exp_f32_e32 v147, v147
	v_exp_f32_e32 v148, v148
	v_mfma_f32_32x32x16_bf16 v[130:145], v[230:233], v[194:197], v[130:145]
	ds_read_b64_tr_b16 v[230:231], v250 offset:24576
	ds_read_b64_tr_b16 v[232:233], v251 offset:24576
	v_exp_f32_e32 v149, v149
	v_add_f32_e32 v213, v213, v146
	v_add_f32_e32 v213, v213, v147
	v_add_f32_e32 v213, v213, v148
	v_add_f32_e32 v213, v213, v149
	s_waitcnt lgkmcnt(6)
	v_mfma_f32_32x32x16_bf16 v[114:129], v[198:201], v[214:217], v[114:129]
	v_exp_f32_e32 v150, v150
	v_exp_f32_e32 v151, v151
	v_exp_f32_e32 v152, v152
	v_mfma_f32_32x32x16_bf16 v[50:65], v[198:201], v[218:221], v[50:65]
	ds_read_b64_tr_b16 v[198:199], v234 offset:28672
	ds_read_b64_tr_b16 v[200:201], v235 offset:28672
	v_exp_f32_e32 v153, v153
	v_add_f32_e32 v213, v213, v150
	v_add_f32_e32 v213, v213, v151
	v_add_f32_e32 v213, v213, v152
	s_waitcnt lgkmcnt(6)
	v_mfma_f32_32x32x16_bf16 v[98:113], v[202:205], v[214:217], v[98:113]
	v_add_f32_e32 v213, v213, v153
	v_exp_f32_e32 v154, v154
	v_exp_f32_e32 v155, v155
	v_mfma_f32_32x32x16_bf16 v[34:49], v[202:205], v[218:221], v[34:49]
	ds_read_b64_tr_b16 v[202:203], v237 offset:28672
	ds_read_b64_tr_b16 v[204:205], v236 offset:28672
	v_exp_f32_e32 v156, v156
	v_exp_f32_e32 v157, v157
	v_add_f32_e32 v213, v213, v154
	s_waitcnt lgkmcnt(6)
; #define LAS __attribute__((address_space(3)))
; __device__ __forceinline__ void diff_attn_phase(const Params& p, LAS unsigned char* lds) {
;     ...
;                 for (int ks = 0; ks < 4; ++ks) kf[ks] = *(const LAS bf16x8*)(Ku + kbase + (kxl ^ (32 * ks)));
;                 bf16x8 P[2][2];
; #pragma unroll
;                 for (int r = 0; r < 2; ++r) {
;                     f32x16 S;
; #pragma unroll
;                     for (int i = 0; i < 16; ++i) S[i] = 0.f;
; #pragma unroll
;                     for (int ks = 0; ks < 4; ++ks) S = __builtin_amdgcn_mfma_f32_32x32x16_bf16(kf[ks], qf[r][ks], S, 0, 0, 0);
;                     S = __builtin_amdgcn_mfma_f32_32x32x16_bf16(kone, qm[r], S, 0, 0, 0);
; #pragma unroll
;                     for (int i = 0; i < 16; ++i) S[i] = __builtin_amdgcn_exp2f(S[i]);
;                     l[r] += sum16(S);
;                     P[r][0] = pack8(S, 0); P[r][1] = pack8(S, 8);
;                 }
; #pragma unroll
;                 for (int t = 0; t < 4; ++t) {
;                     const LAS unsigned char* a0 = Vu + (vb0l ^ (64 * t)); const LAS unsigned char* a1 = Vu + (vb1l ^ (64 * t));
;                     const bf16x8 v0 = tr_pair(a0, a1), v1 = tr_pair(a0 + 4096, a1 + 4096);
;                     O[0][t] = __builtin_amdgcn_mfma_f32_32x32x16_bf16(v0, P[0][0], O[0][t], 0, 0, 0);
;                     O[1][t] = __builtin_amdgcn_mfma_f32_32x32x16_bf16(v0, P[1][0], O[1][t], 0, 0, 0);
;                     O[0][t] = __builtin_amdgcn_mfma_f32_32x32x16_bf16(v1, P[0][1], O[0][t], 0, 0, 0);
;                     O[1][t] = __builtin_amdgcn_mfma_f32_32x32x16_bf16(v1, P[1][1], O[1][t], 0, 0, 0);
	v_mfma_f32_32x32x16_bf16 v[82:97], v[208:211], v[214:217], v[82:97]
	v_add_f32_e32 v213, v213, v155
	v_add_f32_e32 v213, v213, v156
	v_add_f32_e32 v213, v213, v157
	v_exp_f32_e32 v158, v158
	v_mfma_f32_32x32x16_bf16 v[18:33], v[208:211], v[218:221], v[18:33]
	ds_read_b64_tr_b16 v[208:209], v238 offset:28672
	ds_read_b64_tr_b16 v[210:211], v239 offset:28672
	v_exp_f32_e32 v159, v159
	v_exp_f32_e32 v160, v160
	v_exp_f32_e32 v161, v161
	s_waitcnt lgkmcnt(6)
	v_mfma_f32_32x32x16_bf16 v[66:81], v[230:233], v[214:217], v[66:81]
	v_add_f32_e32 v213, v213, v158
	v_add_f32_e32 v213, v213, v159
	v_add_f32_e32 v213, v213, v160
	v_add_f32_e32 v213, v213, v161
	v_exp_f32_e32 v130, v130
	v_mfma_f32_32x32x16_bf16 v[2:17], v[230:233], v[218:221], v[2:17]
	ds_read_b64_tr_b16 v[230:231], v250 offset:28672
	ds_read_b64_tr_b16 v[232:233], v251 offset:28672
	v_exp_f32_e32 v131, v131
	v_exp_f32_e32 v132, v132
	v_exp_f32_e32 v133, v133
	v_add_u32_e32 v234, s37, v234
	v_add_u32_e32 v235, s37, v235
	v_add_u32_e32 v237, s37, v237
	v_add_u32_e32 v236, s37, v236
	v_add_u32_e32 v238, s37, v238
	v_add_u32_e32 v239, s37, v239
	v_add_u32_e32 v250, s37, v250
	v_add_u32_e32 v251, s37, v251
	s_waitcnt lgkmcnt(6)
	v_mfma_f32_32x32x16_bf16 v[114:129], v[198:201], v[222:225], v[114:129]
	v_add_f32_e32 v212, v212, v130
	v_add_f32_e32 v212, v212, v131
	v_add_f32_e32 v212, v212, v132
	v_add_f32_e32 v212, v212, v133
	v_exp_f32_e32 v134, v134
	v_mfma_f32_32x32x16_bf16 v[50:65], v[198:201], v[226:229], v[50:65]
	v_add_u32_e32 v198, v246, v1
	ds_read_b128 v[198:201], v198 offset:8192
	v_exp_f32_e32 v135, v135
	v_exp_f32_e32 v136, v136
	v_exp_f32_e32 v137, v137
	s_waitcnt lgkmcnt(5)
	v_mfma_f32_32x32x16_bf16 v[98:113], v[202:205], v[222:225], v[98:113]
	v_add_f32_e32 v212, v212, v134
	v_add_f32_e32 v212, v212, v135
	v_add_f32_e32 v212, v212, v136
	v_add_f32_e32 v212, v212, v137
	v_mfma_f32_32x32x16_bf16 v[34:49], v[202:205], v[226:229], v[34:49]
	v_xad_u32 v202, v246, 32, v1
	ds_read_b128 v[202:205], v202 offset:8192
	v_cvt_pk_bf16_f32 v214, v146, v147
	v_cvt_pk_bf16_f32 v215, v148, v149
	v_cvt_pk_bf16_f32 v216, v150, v151
	v_cvt_pk_bf16_f32 v217, v152, v153
	s_waitcnt lgkmcnt(4)
	v_mfma_f32_32x32x16_bf16 v[82:97], v[208:211], v[222:225], v[82:97]
	v_cvt_pk_bf16_f32 v218, v130, v131
	v_cvt_pk_bf16_f32 v219, v132, v133
	v_cvt_pk_bf16_f32 v220, v134, v135
	v_cvt_pk_bf16_f32 v221, v136, v137
	v_mfma_f32_32x32x16_bf16 v[18:33], v[208:211], v[226:229], v[18:33]
	v_xad_u32 v208, v246, 64, v1
	ds_read_b128 v[208:211], v208 offset:8192
	v_exp_f32_e32 v138, v138
	v_exp_f32_e32 v139, v139
	s_waitcnt lgkmcnt(3)
	v_mfma_f32_32x32x16_bf16 v[66:81], v[230:233], v[222:225], v[66:81]
	v_exp_f32_e32 v140, v140
	v_exp_f32_e32 v141, v141
	v_add_f32_e32 v212, v212, v138
	v_add_f32_e32 v212, v212, v139
	v_add_f32_e32 v212, v212, v140
	v_add_f32_e32 v212, v212, v141
	v_cvt_pk_bf16_f32 v222, v154, v155
	v_cvt_pk_bf16_f32 v223, v156, v157
	v_cvt_pk_bf16_f32 v224, v158, v159
	v_cvt_pk_bf16_f32 v225, v160, v161
	v_mfma_f32_32x32x16_bf16 v[2:17], v[230:233], v[226:229], v[2:17]
	v_xad_u32 v230, v246, s47, v1
	ds_read_b128 v[230:233], v230 offset:8192
	s_add_i32 s29, s29, 1
	s_branch .Lfb_loopF
; #define LAS __attribute__((address_space(3)))
; __device__ __forceinline__ void diff_attn_phase(const Params& p, LAS unsigned char* lds) {
;     ...
;                 for (int ks = 0; ks < 4; ++ks) kf[ks] = *(const LAS bf16x8*)(Ku + kbase + (kxl ^ (32 * ks)));
;                 bf16x8 P[2][2];
; #pragma unroll
;                 for (int r = 0; r < 2; ++r) {
;                     f32x16 S;
; #pragma unroll
;                     for (int i = 0; i < 16; ++i) S[i] = 0.f;
; #pragma unroll
;                     for (int ks = 0; ks < 4; ++ks) S = __builtin_amdgcn_mfma_f32_32x32x16_bf16(kf[ks], qf[r][ks], S, 0, 0, 0);
;                     S = __builtin_amdgcn_mfma_f32_32x32x16_bf16(kone, qm[r], S, 0, 0, 0);
; #pragma unroll
;                     for (int i = 0; i < 16; ++i) S[i] = __builtin_amdgcn_exp2f(S[i]);
;                     l[r] += sum16(S);
;                     P[r][0] = pack8(S, 0); P[r][1] = pack8(S, 8);
;                 }
; #pragma unroll
;                 for (int t = 0; t < 4; ++t) {
;                     const LAS unsigned char* a0 = Vu + (vb0l ^ (64 * t)); const LAS unsigned char* a1 = Vu + (vb1l ^ (64 * t));
;                     const bf16x8 v0 = tr_pair(a0, a1), v1 = tr_pair(a0 + 4096, a1 + 4096);
;                     O[0][t] = __builtin_amdgcn_mfma_f32_32x32x16_bf16(v0, P[0][0], O[0][t], 0, 0, 0);
;                     O[1][t] = __builtin_amdgcn_mfma_f32_32x32x16_bf16(v0, P[1][0], O[1][t], 0, 0, 0);
;                     O[0][t] = __builtin_amdgcn_mfma_f32_32x32x16_bf16(v1, P[0][1], O[0][t], 0, 0, 0);
;                     O[1][t] = __builtin_amdgcn_mfma_f32_32x32x16_bf16(v1, P[1][1], O[1][t], 0, 0, 0);
;                 }
;             }
;         }
.Lfb_last0F:
	s_waitcnt lgkmcnt(6)
	v_mfma_f32_32x32x16_bf16 v[114:129], v[198:201], v[222:225], v[114:129]
	v_add_f32_e32 v212, v212, v130
	v_add_f32_e32 v212, v212, v131
	v_add_f32_e32 v212, v212, v132
	v_add_f32_e32 v212, v212, v133
	v_exp_f32_e32 v134, v134
	v_mfma_f32_32x32x16_bf16 v[50:65], v[198:201], v[226:229], v[50:65]
	ds_read_b64_tr_b16 v[198:199], v234 offset:24576
	ds_read_b64_tr_b16 v[200:201], v235 offset:24576
	v_exp_f32_e32 v135, v135
	v_exp_f32_e32 v136, v136
	v_exp_f32_e32 v137, v137
	s_waitcnt lgkmcnt(6)
	v_mfma_f32_32x32x16_bf16 v[98:113], v[202:205], v[222:225], v[98:113]
	v_add_f32_e32 v212, v212, v134
	v_add_f32_e32 v212, v212, v135
	v_add_f32_e32 v212, v212, v136
	v_add_f32_e32 v212, v212, v137
	v_mfma_f32_32x32x16_bf16 v[34:49], v[202:205], v[226:229], v[34:49]
	ds_read_b64_tr_b16 v[202:203], v237 offset:24576
	ds_read_b64_tr_b16 v[204:205], v236 offset:24576
	v_cvt_pk_bf16_f32 v214, v146, v147
	v_cvt_pk_bf16_f32 v215, v148, v149
	v_cvt_pk_bf16_f32 v216, v150, v151
	v_cvt_pk_bf16_f32 v217, v152, v153
	s_waitcnt lgkmcnt(6)
	v_mfma_f32_32x32x16_bf16 v[82:97], v[208:211], v[222:225], v[82:97]
	v_cvt_pk_bf16_f32 v218, v130, v131
	v_cvt_pk_bf16_f32 v219, v132, v133
	v_cvt_pk_bf16_f32 v220, v134, v135
	v_cvt_pk_bf16_f32 v221, v136, v137
	v_mfma_f32_32x32x16_bf16 v[18:33], v[208:211], v[226:229], v[18:33]
	ds_read_b64_tr_b16 v[208:209], v238 offset:24576
	ds_read_b64_tr_b16 v[210:211], v239 offset:24576
	v_exp_f32_e32 v138, v138
	v_exp_f32_e32 v139, v139
	s_waitcnt lgkmcnt(6)
	v_mfma_f32_32x32x16_bf16 v[66:81], v[230:233], v[222:225], v[66:81]
	v_exp_f32_e32 v140, v140
	v_exp_f32_e32 v141, v141
	v_add_f32_e32 v212, v212, v138
	v_add_f32_e32 v212, v212, v139
	v_add_f32_e32 v212, v212, v140
	v_add_f32_e32 v212, v212, v141
	v_cvt_pk_bf16_f32 v222, v154, v155
	v_cvt_pk_bf16_f32 v223, v156, v157
	v_cvt_pk_bf16_f32 v224, v158, v159
	v_cvt_pk_bf16_f32 v225, v160, v161
	v_mfma_f32_32x32x16_bf16 v[2:17], v[230:233], v[226:229], v[2:17]
	ds_read_b64_tr_b16 v[230:231], v250 offset:24576
	ds_read_b64_tr_b16 v[232:233], v251 offset:24576
	v_exp_f32_e32 v142, v142
	v_exp_f32_e32 v143, v143
	v_exp_f32_e32 v144, v144
	v_exp_f32_e32 v145, v145
	v_add_f32_e32 v212, v212, v142
	v_add_f32_e32 v212, v212, v143
	v_add_f32_e32 v212, v212, v144
	v_add_f32_e32 v212, v212, v145
	v_cvt_pk_bf16_f32 v226, v138, v139
	v_cvt_pk_bf16_f32 v227, v140, v141
	v_cvt_pk_bf16_f32 v228, v142, v143
	v_cvt_pk_bf16_f32 v229, v144, v145
	s_waitcnt lgkmcnt(6)
	v_mfma_f32_32x32x16_bf16 v[114:129], v[198:201], v[214:217], v[114:129]
	v_mfma_f32_32x32x16_bf16 v[50:65], v[198:201], v[218:221], v[50:65]
	ds_read_b64_tr_b16 v[198:199], v234 offset:28672
	ds_read_b64_tr_b16 v[200:201], v235 offset:28672
	s_waitcnt lgkmcnt(6)
	v_mfma_f32_32x32x16_bf16 v[98:113], v[202:205], v[214:217], v[98:113]
	v_mfma_f32_32x32x16_bf16 v[34:49], v[202:205], v[218:221], v[34:49]
	ds_read_b64_tr_b16 v[202:203], v237 offset:28672
	ds_read_b64_tr_b16 v[204:205], v236 offset:28672
	s_waitcnt lgkmcnt(6)
	v_mfma_f32_32x32x16_bf16 v[82:97], v[208:211], v[214:217], v[82:97]
	v_mfma_f32_32x32x16_bf16 v[18:33], v[208:211], v[218:221], v[18:33]
	ds_read_b64_tr_b16 v[208:209], v238 offset:28672
	ds_read_b64_tr_b16 v[210:211], v239 offset:28672
	s_waitcnt lgkmcnt(6)
	v_mfma_f32_32x32x16_bf16 v[66:81], v[230:233], v[214:217], v[66:81]
	v_mfma_f32_32x32x16_bf16 v[2:17], v[230:233], v[218:221], v[2:17]
	ds_read_b64_tr_b16 v[230:231], v250 offset:28672
	ds_read_b64_tr_b16 v[232:233], v251 offset:28672
	s_waitcnt lgkmcnt(6)
	v_mfma_f32_32x32x16_bf16 v[114:129], v[198:201], v[222:225], v[114:129]
	v_mfma_f32_32x32x16_bf16 v[50:65], v[198:201], v[226:229], v[50:65]
	s_waitcnt lgkmcnt(4)
	v_mfma_f32_32x32x16_bf16 v[98:113], v[202:205], v[222:225], v[98:113]
	v_mfma_f32_32x32x16_bf16 v[34:49], v[202:205], v[226:229], v[34:49]
	s_waitcnt lgkmcnt(2)
	v_mfma_f32_32x32x16_bf16 v[82:97], v[208:211], v[222:225], v[82:97]
	v_mfma_f32_32x32x16_bf16 v[18:33], v[208:211], v[226:229], v[18:33]
	s_waitcnt lgkmcnt(0)
	v_mfma_f32_32x32x16_bf16 v[66:81], v[230:233], v[222:225], v[66:81]
	v_mfma_f32_32x32x16_bf16 v[2:17], v[230:233], v[226:229], v[2:17]
	s_branch .Lad_epi
